# GEMM: first K-loop iteration peeled with SrcC=0 on each accumulator's first MFMA, per-tile zeroing of the 128 accumulator VGPRs removed
# baseline (speedup 1.0000x reference)
; #define PG8_STAGE(bufoff, gbase, voff) do { _Pragma("unroll") for (int _i = 0; _i < 2; ++_i) \
;         __builtin_amdgcn_global_load_lds((const unsigned*)((const char*)(gbase) + (voff)[_i]), (LAS unsigned*)(lds + (bufoff) + ldsw + _i * 8192), 16, 0, 0); } while (0)
; #define PG8_LDA(dst, b, h) do { _Pragma("unroll") for (int m = 0; m < 4; ++m) _Pragma("unroll") for (int k = 0; k < 2; ++k) dst[m][k] = *(const LAS bf16x8*)(lds + PG8_SA(b, h) + aoff + m * 2048 + k * 1024); } while (0)
; #define PG8_LDB(dst, b, h) do { _Pragma("unroll") for (int n = 0; n < 2; ++n) _Pragma("unroll") for (int k = 0; k < 2; ++k) dst[n][k] = *(const LAS bf16x8*)(lds + PG8_SB(b, h) + boff + n * 2048 + k * 1024); } while (0)
; #define PG8_MMA(ai, bj, At, Bt) do { __builtin_amdgcn_s_setprio(1); _Pragma("unroll") for (int m = 0; m < 4; ++m) _Pragma("unroll") for (int n = 0; n < 2; ++n) _Pragma("unroll") for (int k = 0; k < 2; ++k) \
;         acc[ai][bj][m][n] = __builtin_amdgcn_mfma_f32_16x16x32_bf16(Bt[n][k], At[m][k], acc[ai][bj][m][n], 0, 0, 0); __builtin_amdgcn_s_setprio(0); } while (0)
; #define PG8_WAIT_V(n) asm volatile("s_waitcnt vmcnt(" #n ")" ::: "memory")
; #define PG8_WAIT_L(n) asm volatile("s_waitcnt lgkmcnt(" #n ")" ::: "memory")
; #define PG8_BAR __builtin_amdgcn_s_barrier()
; #define PG8_SCHED __builtin_amdgcn_sched_barrier(0)
; __device__ __forceinline__ void gemm_phase(LAS unsigned char* lds, const Gemm g, const StaticOrder& S, const Epi& E) {
;     ...
;             const bool last = (t == nt - 2);
;             const char* a1 = cA + (size_t)(t + 1) * kstep;
;             const char* a2 = last ? nA : cA + (size_t)(t + 2) * kstep; const char* b2 = last ? nB : cB + (size_t)(t + 2) * kstep;
;             const char* a3 = a2 + kstep; const char* b3 = b2 + kstep;
;             PG8_LDB(B0, 0, 0); PG8_LDB(B1, 0, 1); PG8_SCHED; PG8_LDA(At, 0, 0); PG8_STAGE(PG8_SA(1, 1), a1 + hstepA, voffA);
;             PG8_WAIT_V(8); PG8_WAIT_L(0); PG8_BAR; PG8_MMA(0, 0, At, B0); PG8_MMA(0, 1, At, B1); PG8_BAR; PG8_SCHED;
;             PG8_LDA(At, 0, 1); PG8_STAGE(PG8_SB(0, 0), b2, voffB); PG8_STAGE(PG8_SB(0, 1), b2 + hstepB, voffB); PG8_STAGE(PG8_SA(0, 0), a2, voffA);
;             PG8_WAIT_V(8); PG8_WAIT_L(0); PG8_BAR; PG8_MMA(1, 0, At, B0); PG8_MMA(1, 1, At, B1); PG8_BAR; PG8_SCHED;
.LBB0_117:
	s_add_u32 s13, s66, 0x100
	s_addc_u32 s66, s67, 0
	s_add_u32 s8, s64, 0x80
	s_addc_u32 s9, s65, 0
	s_mov_b32 s64, 0
	s_add_i32 s67, s64, 2
	s_add_u32 vcc_lo, s8, 0x80
	s_addc_u32 s65, s9, 0
	s_add_i32 s62, 0, 0x10000
	s_cmp_eq_u32 s76, s64
	s_cselect_b32 s65, s75, s65
	s_cselect_b32 s64, s74, vcc_lo
	v_add_u32_e32 v96, s62, v181
	s_cselect_b32 vcc_hi, s81, s66
	s_cselect_b32 vcc_lo, s80, s13
	s_add_i32 s63, 0, 0x14000
	ds_read_b128 v[130:133], v96
	ds_read_b128 v[134:137], v96 offset:1024
	ds_read_b128 v[138:141], v96 offset:2048
	ds_read_b128 v[142:145], v96 offset:3072
	v_add_u32_e32 v96, s63, v181
	ds_read_b128 v[146:149], v96
	ds_read_b128 v[150:153], v96 offset:1024
	ds_read_b128 v[168:171], v96 offset:2048
	ds_read_b128 v[172:175], v96 offset:3072
	v_lshl_add_u64 v[238:239], s[8:9], 0, v[166:167]
	s_add_i32 m0, s58, 0xc000
	ds_read_b128 v[176:179], v208
	ds_read_b128 v[210:213], v208 offset:1024
	ds_read_b128 v[214:217], v208 offset:2048
	ds_read_b128 v[218:221], v208 offset:3072
	ds_read_b128 v[222:225], v208 offset:4096
	ds_read_b128 v[226:229], v208 offset:5120
	ds_read_b128 v[230:233], v208 offset:6144
	ds_read_b128 v[234:237], v208 offset:7168
	global_load_lds_dwordx4 v[238:239], off
	v_lshl_add_u64 v[238:239], s[8:9], 0, v[164:165]
	s_add_i32 m0, s58, 0xe000
	s_nop 0
	global_load_lds_dwordx4 v[238:239], off
	s_waitcnt vmcnt(8)
	s_waitcnt lgkmcnt(0)
	s_barrier
	s_setprio 1
	s_waitcnt lgkmcnt(0)
	v_mfma_f32_16x16x32_bf16 v[126:129], v[130:133], v[176:179], 0
	v_mfma_f32_16x16x32_bf16 v[122:125], v[138:141], v[176:179], 0
	v_mfma_f32_16x16x32_bf16 v[110:113], v[130:133], v[214:217], 0
	v_mfma_f32_16x16x32_bf16 v[106:109], v[138:141], v[214:217], 0
	v_mfma_f32_16x16x32_bf16 v[92:95], v[130:133], v[222:225], 0
	v_mfma_f32_16x16x32_bf16 v[88:91], v[138:141], v[222:225], 0
	v_mfma_f32_16x16x32_bf16 v[76:79], v[130:133], v[230:233], 0
	v_mfma_f32_16x16x32_bf16 v[72:75], v[138:141], v[230:233], 0
	v_mfma_f32_16x16x32_bf16 v[126:129], v[134:137], v[210:213], v[126:129]
	v_mfma_f32_16x16x32_bf16 v[122:125], v[142:145], v[210:213], v[122:125]
	v_mfma_f32_16x16x32_bf16 v[110:113], v[134:137], v[218:221], v[110:113]
	v_mfma_f32_16x16x32_bf16 v[106:109], v[142:145], v[218:221], v[106:109]
	v_mfma_f32_16x16x32_bf16 v[92:95], v[134:137], v[226:229], v[92:95]
	v_mfma_f32_16x16x32_bf16 v[88:91], v[142:145], v[226:229], v[88:91]
	v_mfma_f32_16x16x32_bf16 v[76:79], v[134:137], v[234:237], v[76:79]
	v_mfma_f32_16x16x32_bf16 v[72:75], v[142:145], v[234:237], v[72:75]
	s_setprio 0
	s_setprio 1
	v_mfma_f32_16x16x32_bf16 v[118:121], v[146:149], v[176:179], 0
	v_mfma_f32_16x16x32_bf16 v[114:117], v[168:171], v[176:179], 0
	v_mfma_f32_16x16x32_bf16 v[102:105], v[146:149], v[214:217], 0
	v_mfma_f32_16x16x32_bf16 v[98:101], v[168:171], v[214:217], 0
	v_mfma_f32_16x16x32_bf16 v[84:87], v[146:149], v[222:225], 0
	v_mfma_f32_16x16x32_bf16 v[80:83], v[168:171], v[222:225], 0
	v_mfma_f32_16x16x32_bf16 v[68:71], v[146:149], v[230:233], 0
	v_mfma_f32_16x16x32_bf16 v[64:67], v[168:171], v[230:233], 0
	v_mfma_f32_16x16x32_bf16 v[118:121], v[150:153], v[210:213], v[118:121]
	v_mfma_f32_16x16x32_bf16 v[114:117], v[172:175], v[210:213], v[114:117]
	v_mfma_f32_16x16x32_bf16 v[102:105], v[150:153], v[218:221], v[102:105]
	v_mfma_f32_16x16x32_bf16 v[98:101], v[172:175], v[218:221], v[98:101]
	v_mfma_f32_16x16x32_bf16 v[84:87], v[150:153], v[226:229], v[84:87]
	v_mfma_f32_16x16x32_bf16 v[80:83], v[172:175], v[226:229], v[80:83]
	v_mfma_f32_16x16x32_bf16 v[68:71], v[150:153], v[234:237], v[68:71]
	v_mfma_f32_16x16x32_bf16 v[64:67], v[172:175], v[234:237], v[64:67]
	s_setprio 0
	s_barrier
	s_add_i32 s62, s62, s15
	v_lshl_add_u64 v[238:239], vcc, 0, v[156:157]
	s_mov_b32 m0, s62
	ds_read_b128 v[176:179], v208 offset:16384
	ds_read_b128 v[210:213], v208 offset:17408
	ds_read_b128 v[214:217], v208 offset:18432
	ds_read_b128 v[218:221], v208 offset:19456
	ds_read_b128 v[222:225], v208 offset:20480
	ds_read_b128 v[226:229], v208 offset:21504
	ds_read_b128 v[230:233], v208 offset:22528
	ds_read_b128 v[234:237], v208 offset:23552
	global_load_lds_dwordx4 v[238:239], off
	s_add_i32 m0, s62, 0x2000
	v_lshl_add_u64 v[240:241], vcc, 0, v[160:161]
	s_add_u32 vcc_lo, vcc_lo, s4
	s_addc_u32 vcc_hi, vcc_hi, s5
	s_add_i32 s62, s63, s15
	global_load_lds_dwordx4 v[240:241], off
	v_lshl_add_u64 v[242:243], vcc, 0, v[156:157]
	s_mov_b32 m0, s62
	v_lshl_add_u64 v[244:245], vcc, 0, v[160:161]
	global_load_lds_dwordx4 v[242:243], off
	s_add_i32 m0, s62, 0x2000
	v_lshl_add_u64 v[246:247], s[64:65], 0, v[154:155]
	global_load_lds_dwordx4 v[244:245], off
	s_mov_b32 m0, s58
	v_lshl_add_u64 v[248:249], s[64:65], 0, v[158:159]
	global_load_lds_dwordx4 v[246:247], off
	s_mov_b32 m0, s84
	s_nop 0
	global_load_lds_dwordx4 v[248:249], off
	s_waitcnt vmcnt(8)
	s_waitcnt lgkmcnt(0)
	s_barrier
; #define PG8_STAGE(bufoff, gbase, voff) do { _Pragma("unroll") for (int _i = 0; _i < 2; ++_i) \
;         __builtin_amdgcn_global_load_lds((const unsigned*)((const char*)(gbase) + (voff)[_i]), (LAS unsigned*)(lds + (bufoff) + ldsw + _i * 8192), 16, 0, 0); } while (0)
; #define PG8_LDA(dst, b, h) do { _Pragma("unroll") for (int m = 0; m < 4; ++m) _Pragma("unroll") for (int k = 0; k < 2; ++k) dst[m][k] = *(const LAS bf16x8*)(lds + PG8_SA(b, h) + aoff + m * 2048 + k * 1024); } while (0)
; #define PG8_LDB(dst, b, h) do { _Pragma("unroll") for (int n = 0; n < 2; ++n) _Pragma("unroll") for (int k = 0; k < 2; ++k) dst[n][k] = *(const LAS bf16x8*)(lds + PG8_SB(b, h) + boff + n * 2048 + k * 1024); } while (0)
; #define PG8_MMA(ai, bj, At, Bt) do { __builtin_amdgcn_s_setprio(1); _Pragma("unroll") for (int m = 0; m < 4; ++m) _Pragma("unroll") for (int n = 0; n < 2; ++n) _Pragma("unroll") for (int k = 0; k < 2; ++k) \
;         acc[ai][bj][m][n] = __builtin_amdgcn_mfma_f32_16x16x32_bf16(Bt[n][k], At[m][k], acc[ai][bj][m][n], 0, 0, 0); __builtin_amdgcn_s_setprio(0); } while (0)
; #define PG8_WAIT_V(n) asm volatile("s_waitcnt vmcnt(" #n ")" ::: "memory")
; #define PG8_WAIT_L(n) asm volatile("s_waitcnt lgkmcnt(" #n ")" ::: "memory")
; #define PG8_BAR __builtin_amdgcn_s_barrier()
; #define PG8_SCHED __builtin_amdgcn_sched_barrier(0)
; __device__ __forceinline__ void gemm_phase(LAS unsigned char* lds, const Gemm g, const StaticOrder& S, const Epi& E) {
;     ...
;             PG8_WAIT_V(8); PG8_WAIT_L(0); PG8_BAR; PG8_MMA(1, 0, At, B0); PG8_MMA(1, 1, At, B1); PG8_BAR; PG8_SCHED;
;             PG8_LDB(B0, 1, 0); PG8_LDB(B1, 1, 1); PG8_SCHED; PG8_LDA(At, 1, 0); PG8_STAGE(PG8_SA(0, 1), a2 + hstepA, voffA);
;             PG8_WAIT_V(8); PG8_WAIT_L(0); PG8_BAR; PG8_MMA(0, 0, At, B0); PG8_MMA(0, 1, At, B1); PG8_BAR; PG8_SCHED;
	s_setprio 1
	s_waitcnt lgkmcnt(0)
	v_mfma_f32_16x16x32_bf16 v[60:63], v[130:133], v[176:179], 0
	v_mfma_f32_16x16x32_bf16 v[56:59], v[138:141], v[176:179], 0
	v_mfma_f32_16x16x32_bf16 v[44:47], v[130:133], v[214:217], 0
	v_mfma_f32_16x16x32_bf16 v[40:43], v[138:141], v[214:217], 0
	v_mfma_f32_16x16x32_bf16 v[28:31], v[130:133], v[222:225], 0
	v_mfma_f32_16x16x32_bf16 v[24:27], v[138:141], v[222:225], 0
	v_mfma_f32_16x16x32_bf16 v[12:15], v[130:133], v[230:233], 0
	v_mfma_f32_16x16x32_bf16 v[8:11], v[138:141], v[230:233], 0
	v_mfma_f32_16x16x32_bf16 v[60:63], v[134:137], v[210:213], v[60:63]
	v_mfma_f32_16x16x32_bf16 v[56:59], v[142:145], v[210:213], v[56:59]
	v_mfma_f32_16x16x32_bf16 v[44:47], v[134:137], v[218:221], v[44:47]
	v_mfma_f32_16x16x32_bf16 v[40:43], v[142:145], v[218:221], v[40:43]
	v_mfma_f32_16x16x32_bf16 v[28:31], v[134:137], v[226:229], v[28:31]
	v_mfma_f32_16x16x32_bf16 v[24:27], v[142:145], v[226:229], v[24:27]
	v_mfma_f32_16x16x32_bf16 v[12:15], v[134:137], v[234:237], v[12:15]
	v_mfma_f32_16x16x32_bf16 v[8:11], v[142:145], v[234:237], v[8:11]
	s_setprio 0
	s_setprio 1
	v_mfma_f32_16x16x32_bf16 v[52:55], v[146:149], v[176:179], 0
	v_mfma_f32_16x16x32_bf16 v[48:51], v[168:171], v[176:179], 0
	v_mfma_f32_16x16x32_bf16 v[36:39], v[146:149], v[214:217], 0
	v_mfma_f32_16x16x32_bf16 v[32:35], v[168:171], v[214:217], 0
	v_mfma_f32_16x16x32_bf16 v[20:23], v[146:149], v[222:225], 0
	v_mfma_f32_16x16x32_bf16 v[16:19], v[168:171], v[222:225], 0
	v_mfma_f32_16x16x32_bf16 v[4:7], v[146:149], v[230:233], 0
	v_mfma_f32_16x16x32_bf16 v[0:3], v[168:171], v[230:233], 0
	v_mfma_f32_16x16x32_bf16 v[52:55], v[150:153], v[210:213], v[52:55]
	v_mfma_f32_16x16x32_bf16 v[48:51], v[172:175], v[210:213], v[48:51]
	v_mfma_f32_16x16x32_bf16 v[36:39], v[150:153], v[218:221], v[36:39]
	v_mfma_f32_16x16x32_bf16 v[32:35], v[172:175], v[218:221], v[32:35]
	v_mfma_f32_16x16x32_bf16 v[20:23], v[150:153], v[226:229], v[20:23]
	v_mfma_f32_16x16x32_bf16 v[16:19], v[172:175], v[226:229], v[16:19]
	v_mfma_f32_16x16x32_bf16 v[4:7], v[150:153], v[234:237], v[4:7]
	v_mfma_f32_16x16x32_bf16 v[0:3], v[172:175], v[234:237], v[0:3]
	s_setprio 0
	s_barrier
	s_add_i32 s62, 0, 0x18000
	v_add_u32_e32 v96, s62, v181
	s_add_i32 s63, 0, 0x1c000
	ds_read_b128 v[130:133], v96
	ds_read_b128 v[134:137], v96 offset:1024
	ds_read_b128 v[138:141], v96 offset:2048
	ds_read_b128 v[142:145], v96 offset:3072
	v_add_u32_e32 v96, s63, v181
	ds_read_b128 v[146:149], v96
	ds_read_b128 v[150:153], v96 offset:1024
	ds_read_b128 v[168:171], v96 offset:2048
	ds_read_b128 v[172:175], v96 offset:3072
	s_add_u32 s64, s64, s72
	s_addc_u32 s65, s65, s73
	s_mov_b32 m0, s85
	v_lshl_add_u64 v[250:251], s[64:65], 0, v[154:155]
	ds_read_b128 v[176:179], v208 offset:32768
	ds_read_b128 v[210:213], v208 offset:33792
	ds_read_b128 v[214:217], v208 offset:34816
	ds_read_b128 v[218:221], v208 offset:35840
	ds_read_b128 v[222:225], v208 offset:36864
	ds_read_b128 v[226:229], v208 offset:37888
	ds_read_b128 v[230:233], v208 offset:38912
	ds_read_b128 v[234:237], v208 offset:39936
	global_load_lds_dwordx4 v[250:251], off
	v_lshl_add_u64 v[250:251], s[64:65], 0, v[158:159]
	s_mov_b32 m0, s91
	s_nop 0
	global_load_lds_dwordx4 v[250:251], off
	s_waitcnt vmcnt(8)
	s_waitcnt lgkmcnt(0)
	s_barrier
	s_setprio 1
	s_waitcnt lgkmcnt(0)
	v_mfma_f32_16x16x32_bf16 v[126:129], v[130:133], v[176:179], v[126:129]
	v_mfma_f32_16x16x32_bf16 v[122:125], v[138:141], v[176:179], v[122:125]
	v_mfma_f32_16x16x32_bf16 v[110:113], v[130:133], v[214:217], v[110:113]
	v_mfma_f32_16x16x32_bf16 v[106:109], v[138:141], v[214:217], v[106:109]
	v_mfma_f32_16x16x32_bf16 v[92:95], v[130:133], v[222:225], v[92:95]
	v_mfma_f32_16x16x32_bf16 v[88:91], v[138:141], v[222:225], v[88:91]
	v_mfma_f32_16x16x32_bf16 v[76:79], v[130:133], v[230:233], v[76:79]
	v_mfma_f32_16x16x32_bf16 v[72:75], v[138:141], v[230:233], v[72:75]
	v_mfma_f32_16x16x32_bf16 v[126:129], v[134:137], v[210:213], v[126:129]
	v_mfma_f32_16x16x32_bf16 v[122:125], v[142:145], v[210:213], v[122:125]
	v_mfma_f32_16x16x32_bf16 v[110:113], v[134:137], v[218:221], v[110:113]
	v_mfma_f32_16x16x32_bf16 v[106:109], v[142:145], v[218:221], v[106:109]
	v_mfma_f32_16x16x32_bf16 v[92:95], v[134:137], v[226:229], v[92:95]
	v_mfma_f32_16x16x32_bf16 v[88:91], v[142:145], v[226:229], v[88:91]
	v_mfma_f32_16x16x32_bf16 v[76:79], v[134:137], v[234:237], v[76:79]
	v_mfma_f32_16x16x32_bf16 v[72:75], v[142:145], v[234:237], v[72:75]
	s_setprio 0
	s_setprio 1
	v_mfma_f32_16x16x32_bf16 v[118:121], v[146:149], v[176:179], v[118:121]
	v_mfma_f32_16x16x32_bf16 v[114:117], v[168:171], v[176:179], v[114:117]
	v_mfma_f32_16x16x32_bf16 v[102:105], v[146:149], v[214:217], v[102:105]
	v_mfma_f32_16x16x32_bf16 v[98:101], v[168:171], v[214:217], v[98:101]
	v_mfma_f32_16x16x32_bf16 v[84:87], v[146:149], v[222:225], v[84:87]
	v_mfma_f32_16x16x32_bf16 v[80:83], v[168:171], v[222:225], v[80:83]
	v_mfma_f32_16x16x32_bf16 v[68:71], v[146:149], v[230:233], v[68:71]
	v_mfma_f32_16x16x32_bf16 v[64:67], v[168:171], v[230:233], v[64:67]
	v_mfma_f32_16x16x32_bf16 v[118:121], v[150:153], v[210:213], v[118:121]
	v_mfma_f32_16x16x32_bf16 v[114:117], v[172:175], v[210:213], v[114:117]
	v_mfma_f32_16x16x32_bf16 v[102:105], v[150:153], v[218:221], v[102:105]
	v_mfma_f32_16x16x32_bf16 v[98:101], v[172:175], v[218:221], v[98:101]
	v_mfma_f32_16x16x32_bf16 v[84:87], v[150:153], v[226:229], v[84:87]
	v_mfma_f32_16x16x32_bf16 v[80:83], v[172:175], v[226:229], v[80:83]
	v_mfma_f32_16x16x32_bf16 v[68:71], v[150:153], v[234:237], v[68:71]
	v_mfma_f32_16x16x32_bf16 v[64:67], v[172:175], v[234:237], v[64:67]
	s_setprio 0
	s_barrier
; #define PG8_STAGE(bufoff, gbase, voff) do { _Pragma("unroll") for (int _i = 0; _i < 2; ++_i) \
;         __builtin_amdgcn_global_load_lds((const unsigned*)((const char*)(gbase) + (voff)[_i]), (LAS unsigned*)(lds + (bufoff) + ldsw + _i * 8192), 16, 0, 0); } while (0)
; #define PG8_LDA(dst, b, h) do { _Pragma("unroll") for (int m = 0; m < 4; ++m) _Pragma("unroll") for (int k = 0; k < 2; ++k) dst[m][k] = *(const LAS bf16x8*)(lds + PG8_SA(b, h) + aoff + m * 2048 + k * 1024); } while (0)
; #define PG8_MMA(ai, bj, At, Bt) do { __builtin_amdgcn_s_setprio(1); _Pragma("unroll") for (int m = 0; m < 4; ++m) _Pragma("unroll") for (int n = 0; n < 2; ++n) _Pragma("unroll") for (int k = 0; k < 2; ++k) \
;         acc[ai][bj][m][n] = __builtin_amdgcn_mfma_f32_16x16x32_bf16(Bt[n][k], At[m][k], acc[ai][bj][m][n], 0, 0, 0); __builtin_amdgcn_s_setprio(0); } while (0)
; #define PG8_WAIT_V(n) asm volatile("s_waitcnt vmcnt(" #n ")" ::: "memory")
; #define PG8_WAIT_L(n) asm volatile("s_waitcnt lgkmcnt(" #n ")" ::: "memory")
; #define PG8_BAR __builtin_amdgcn_s_barrier()
; #define PG8_SCHED __builtin_amdgcn_sched_barrier(0)
; __device__ __forceinline__ void gemm_phase(LAS unsigned char* lds, const Gemm g, const StaticOrder& S, const Epi& E) {
;     ...
;             PG8_LDA(At, 1, 1); PG8_STAGE(PG8_SB(1, 0), b3, voffB); PG8_STAGE(PG8_SB(1, 1), b3 + hstepB, voffB); PG8_STAGE(PG8_SA(1, 0), a3, voffA);
;             PG8_WAIT_V(8); PG8_WAIT_L(0); PG8_BAR; PG8_MMA(1, 0, At, B0); PG8_MMA(1, 1, At, B1); PG8_BAR; PG8_SCHED;
;         }
;         if (wr == 0) PG8_BAR;
	s_add_i32 s62, s62, s15
	v_lshl_add_u64 v[238:239], v[238:239], 0, s[68:69]
	s_mov_b32 m0, s62
	ds_read_b128 v[176:179], v208 offset:49152
	ds_read_b128 v[210:213], v208 offset:50176
	ds_read_b128 v[214:217], v208 offset:51200
	ds_read_b128 v[218:221], v208 offset:52224
	ds_read_b128 v[222:225], v208 offset:53248
	ds_read_b128 v[226:229], v208 offset:54272
	ds_read_b128 v[230:233], v208 offset:55296
	ds_read_b128 v[234:237], v208 offset:56320
	global_load_lds_dwordx4 v[238:239], off
	v_lshl_add_u64 v[238:239], v[240:241], 0, s[68:69]
	s_add_i32 m0, s62, 0x2000
	s_add_i32 s62, s63, s15
	global_load_lds_dwordx4 v[238:239], off
	v_lshl_add_u64 v[238:239], v[242:243], 0, s[68:69]
	s_mov_b32 m0, s62
	s_nop 0
	global_load_lds_dwordx4 v[238:239], off
	v_lshl_add_u64 v[238:239], v[244:245], 0, s[68:69]
	s_add_i32 m0, s62, 0x2000
	s_nop 0
	global_load_lds_dwordx4 v[238:239], off
	v_lshl_add_u64 v[238:239], v[246:247], 0, s[68:69]
	s_mov_b32 m0, s82
	s_nop 0
	global_load_lds_dwordx4 v[238:239], off
	v_lshl_add_u64 v[238:239], v[248:249], 0, s[68:69]
	s_mov_b32 m0, s56
	s_nop 0
	global_load_lds_dwordx4 v[238:239], off
	s_waitcnt vmcnt(8)
	s_waitcnt lgkmcnt(0)
	s_barrier
	s_setprio 1
	s_waitcnt lgkmcnt(0)
	v_mfma_f32_16x16x32_bf16 v[60:63], v[130:133], v[176:179], v[60:63]
	v_mfma_f32_16x16x32_bf16 v[56:59], v[138:141], v[176:179], v[56:59]
	v_mfma_f32_16x16x32_bf16 v[44:47], v[130:133], v[214:217], v[44:47]
	v_mfma_f32_16x16x32_bf16 v[40:43], v[138:141], v[214:217], v[40:43]
	v_mfma_f32_16x16x32_bf16 v[28:31], v[130:133], v[222:225], v[28:31]
	v_mfma_f32_16x16x32_bf16 v[24:27], v[138:141], v[222:225], v[24:27]
	v_mfma_f32_16x16x32_bf16 v[12:15], v[130:133], v[230:233], v[12:15]
	v_mfma_f32_16x16x32_bf16 v[8:11], v[138:141], v[230:233], v[8:11]
	v_mfma_f32_16x16x32_bf16 v[60:63], v[134:137], v[210:213], v[60:63]
	v_mfma_f32_16x16x32_bf16 v[56:59], v[142:145], v[210:213], v[56:59]
	v_mfma_f32_16x16x32_bf16 v[44:47], v[134:137], v[218:221], v[44:47]
	v_mfma_f32_16x16x32_bf16 v[40:43], v[142:145], v[218:221], v[40:43]
	v_mfma_f32_16x16x32_bf16 v[28:31], v[134:137], v[226:229], v[28:31]
	v_mfma_f32_16x16x32_bf16 v[24:27], v[142:145], v[226:229], v[24:27]
	v_mfma_f32_16x16x32_bf16 v[12:15], v[134:137], v[234:237], v[12:15]
	v_mfma_f32_16x16x32_bf16 v[8:11], v[142:145], v[234:237], v[8:11]
	s_setprio 0
	s_setprio 1
	v_mfma_f32_16x16x32_bf16 v[52:55], v[146:149], v[176:179], v[52:55]
	v_mfma_f32_16x16x32_bf16 v[48:51], v[168:171], v[176:179], v[48:51]
	v_mfma_f32_16x16x32_bf16 v[36:39], v[146:149], v[214:217], v[36:39]
	v_mfma_f32_16x16x32_bf16 v[32:35], v[168:171], v[214:217], v[32:35]
	v_mfma_f32_16x16x32_bf16 v[20:23], v[146:149], v[222:225], v[20:23]
	v_mfma_f32_16x16x32_bf16 v[16:19], v[168:171], v[222:225], v[16:19]
	v_mfma_f32_16x16x32_bf16 v[4:7], v[146:149], v[230:233], v[4:7]
	v_mfma_f32_16x16x32_bf16 v[0:3], v[168:171], v[230:233], v[0:3]
	v_mfma_f32_16x16x32_bf16 v[52:55], v[150:153], v[210:213], v[52:55]
	v_mfma_f32_16x16x32_bf16 v[48:51], v[172:175], v[210:213], v[48:51]
	v_mfma_f32_16x16x32_bf16 v[36:39], v[150:153], v[218:221], v[36:39]
	v_mfma_f32_16x16x32_bf16 v[32:35], v[172:175], v[218:221], v[32:35]
	v_mfma_f32_16x16x32_bf16 v[20:23], v[150:153], v[226:229], v[20:23]
	v_mfma_f32_16x16x32_bf16 v[16:19], v[172:175], v[226:229], v[16:19]
	v_mfma_f32_16x16x32_bf16 v[4:7], v[150:153], v[234:237], v[4:7]
	v_mfma_f32_16x16x32_bf16 v[0:3], v[172:175], v[234:237], v[0:3]
	s_setprio 0
	s_barrier
	s_add_u32 s13, s13, 0x100
	s_addc_u32 s66, s66, 0
	s_add_u32 s8, s8, 0x100
	s_addc_u32 s9, s9, 0
	s_cmp_ge_u32 s67, s40
	s_mov_b32 s64, s67
	s_cbranch_scc0 .LBB0_118
	s_branch .Lmy_kdone

; #define PG8_BAR __builtin_amdgcn_s_barrier()
; __device__ __forceinline__ void gemm_phase(LAS unsigned char* lds, const Gemm g, const StaticOrder& S, const Epi& E) {
;     ...
;         if (wr == 0) PG8_BAR;
.Lmy_kdone:
	s_and_b64 vcc, exec, s[2:3]
	s_cbranch_vccz .LBB0_121
	s_barrier
